# SEAM0: skip L2 write-back (P0 only publishes memory-side atomics)
# baseline (speedup 1.0000x reference)
; __device__ __forceinline__ unsigned xb_add(unsigned* p, unsigned v) { return __hip_atomic_fetch_add(p, v, __ATOMIC_RELAXED, __HIP_MEMORY_SCOPE_AGENT); }
; __device__ __forceinline__ void xcd_barrier(const XcdBarrier& b) {
;     asm volatile("s_waitcnt vmcnt(0)" ::: "memory");
;     __syncthreads();
;     if (threadIdx.x == 0) {
;         unsigned* bar = b.bar;
;         __builtin_amdgcn_s_waitcnt(0);
;         unsigned nloc = b.st[0], nx = b.st[1];
;         if (nloc == 0u) { xcd_barrier_complete(bar, b.x, b.gsize, nloc, nx); b.st[0] = nloc; b.st[1] = nx; }
;         const unsigned old = xb_add(&bar[XB_XSUB(b.x)], 1u);
;         const unsigned gen = old / nloc;
;         if (old + 1u == (gen + 1u) * nloc) {
;             __builtin_amdgcn_fence(__ATOMIC_RELEASE, "agent");
;             asm volatile("s_waitcnt vmcnt(0)" ::: "memory");
;             const unsigned og = xb_add(&bar[XB_TOP], 1u);
.LBB0_45:
	s_andn2_saveexec_b64 s[8:9], s[8:9]
	s_cbranch_execz .LBB0_65
	s_mov_b64 s[8:9], exec
	s_waitcnt lgkmcnt(0)
	s_waitcnt vmcnt(0)
	v_mbcnt_lo_u32_b32 v2, s8, 0
	v_mbcnt_hi_u32_b32 v2, s9, v2
	v_cmp_eq_u32_e32 vcc, 0, v2
	s_and_saveexec_b64 s[10:11], vcc
	s_cbranch_execz .LBB0_48
	s_bcnt1_i32_b64 s8, s[8:9]
	v_mov_b32_e32 v3, 0x7000
	v_mov_b32_e32 v4, s8
	global_atomic_add v3, v3, v4, s[60:61] offset:1024 sc0
